# v38 + last phase-2 stage skips its three empty 16-token blocks
# baseline (speedup 1.0000x reference)
.LBB0_302:
	s_or_b64 exec, exec, s[0:1]
	s_addk_i32 s33, 0x3900
	s_cmpk_eq_i32 s72, 0x100
	s_cselect_b32 s33, 0xe400, s33
	s_cmpk_eq_u32 s33, 0xe400
	v_add_u32_e32 v186, 16, v186
	s_cbranch_scc1 .LBB0_286
